# projection epilogues: 8 row scales read from LDS together at the top (one round trip), on v027
# speedup vs baseline: 1.0118x; 1.0118x over previous
.LBB0_214:
	s_lshl_b32 s1, s1, 10
	v_add_u32_e32 v160, s1, v156
	ds_read_b32 v155, v160
	ds_read_b32 v174, v160 offset:64
	ds_read_b32 v176, v160 offset:128
	ds_read_b32 v178, v160 offset:192
	ds_read_b32 v180, v160 offset:512
	ds_read_b32 v182, v160 offset:576
	ds_read_b32 v184, v160 offset:640
	ds_read_b32 v186, v160 offset:704
	s_waitcnt lgkmcnt(0)
	s_cmp_gt_i32 s0, 7
	v_lshl_add_u32 v152, s6, 8, v131
	s_cselect_b64 s[50:51], -1, 0
	s_mov_b64 s[6:7], -1
	s_and_b64 vcc, exec, s[50:51]
	v_ashrrev_i32_e32 v153, 31, v152
	v_lshlrev_b32_e32 v142, 1, v132
	s_cbranch_vccz .LBB0_216
	v_lshlrev_b64 v[162:163], 11, v[152:153]
	v_lshl_add_u64 v[162:163], s[20:21], 0, v[162:163]
	s_lshl_b32 s8, s0, 9
	v_lshl_add_u64 v[162:163], v[162:163], 0, s[8:9]
	s_lshl_b32 s8, s67, 1
	v_lshl_add_u64 v[162:163], v[162:163], 0, s[8:9]
	s_waitcnt lgkmcnt(0)
	v_mov_b32_e32 v154, v155
	v_lshl_add_u64 v[166:167], v[162:163], 0, v[142:143]
	v_pk_mul_f32 v[164:165], v[126:127], v[154:155] op_sel_hi:[1,0]
	v_pk_mul_f32 v[162:163], v[124:125], v[154:155] op_sel_hi:[1,0]
	v_pk_mul_f32 v[168:169], v[122:123], v[154:155] op_sel_hi:[1,0]
	v_pk_mul_f32 v[170:171], v[120:121], v[154:155] op_sel_hi:[1,0]
	v_cvt_pk_bf16_f32 v162, v162, v163
	v_cvt_pk_bf16_f32 v163, v164, v165
	s_mov_b64 s[6:7], 0
	v_cvt_pk_bf16_f32 v164, v170, v171
	v_cvt_pk_bf16_f32 v165, v168, v169
	global_store_dwordx4 v[166:167], v[162:165], off offset:-4096
	v_pk_mul_f32 v[168:169], v[114:115], v[154:155] op_sel_hi:[1,0]
	v_pk_mul_f32 v[170:171], v[112:113], v[154:155] op_sel_hi:[1,0]
	v_pk_mul_f32 v[164:165], v[118:119], v[154:155] op_sel_hi:[1,0]
	v_pk_mul_f32 v[162:163], v[116:117], v[154:155] op_sel_hi:[1,0]
	s_nop 0
	v_cvt_pk_bf16_f32 v162, v162, v163
	v_cvt_pk_bf16_f32 v163, v164, v165
	v_cvt_pk_bf16_f32 v164, v170, v171
	v_cvt_pk_bf16_f32 v165, v168, v169
	global_store_dwordx4 v[166:167], v[162:165], off offset:-3840

.LBB0_218:
	s_nop 1
	v_mov_b32_e32 v114, v174
	s_nop 0
	v_or_b32_e32 v112, 16, v152
	v_cndmask_b32_e64 v113, 0, 1, s[50:51]
	s_mov_b64 s[52:53], -1
	v_cmp_ne_u32_e64 s[6:7], 1, v113
	s_andn2_b64 vcc, exec, s[50:51]
	v_ashrrev_i32_e32 v113, 31, v112
	s_cbranch_vccnz .LBB0_220
	v_lshlrev_b64 v[116:117], 11, v[112:113]
	v_lshl_add_u64 v[116:117], s[20:21], 0, v[116:117]
	s_lshl_b32 s8, s0, 9
	v_lshl_add_u64 v[116:117], v[116:117], 0, s[8:9]
	s_lshl_b32 s8, s67, 1
	v_lshl_add_u64 v[116:117], v[116:117], 0, s[8:9]
	v_lshl_add_u64 v[120:121], v[116:117], 0, v[142:143]
	s_waitcnt lgkmcnt(0)
	v_pk_mul_f32 v[118:119], v[110:111], v[114:115] op_sel_hi:[1,0]
	v_pk_mul_f32 v[116:117], v[108:109], v[114:115] op_sel_hi:[1,0]
	v_pk_mul_f32 v[122:123], v[106:107], v[114:115] op_sel_hi:[1,0]
	v_pk_mul_f32 v[124:125], v[104:105], v[114:115] op_sel_hi:[1,0]
	v_cvt_pk_bf16_f32 v116, v116, v117
	v_cvt_pk_bf16_f32 v117, v118, v119
	s_mov_b64 s[52:53], 0
	v_cvt_pk_bf16_f32 v118, v124, v125
	v_cvt_pk_bf16_f32 v119, v122, v123
	global_store_dwordx4 v[120:121], v[116:119], off offset:-4096
	v_pk_mul_f32 v[122:123], v[98:99], v[114:115] op_sel_hi:[1,0]
	v_pk_mul_f32 v[124:125], v[96:97], v[114:115] op_sel_hi:[1,0]
	v_pk_mul_f32 v[118:119], v[102:103], v[114:115] op_sel_hi:[1,0]
	v_pk_mul_f32 v[116:117], v[100:101], v[114:115] op_sel_hi:[1,0]
	s_nop 0
	v_cvt_pk_bf16_f32 v116, v116, v117
	v_cvt_pk_bf16_f32 v117, v118, v119
	v_cvt_pk_bf16_f32 v118, v124, v125
	v_cvt_pk_bf16_f32 v119, v122, v123
	global_store_dwordx4 v[120:121], v[116:119], off offset:-3840

.LBB0_222:
	s_nop 1
	v_mov_b32_e32 v98, v176
	s_nop 0
	v_or_b32_e32 v96, 32, v152
	s_mov_b64 s[50:51], -1
	s_and_b64 vcc, exec, s[6:7]
	v_ashrrev_i32_e32 v97, 31, v96
	s_cbranch_vccnz .LBB0_224
	v_lshlrev_b64 v[100:101], 11, v[96:97]
	v_lshl_add_u64 v[100:101], s[20:21], 0, v[100:101]
	s_lshl_b32 s8, s0, 9
	v_lshl_add_u64 v[100:101], v[100:101], 0, s[8:9]
	s_lshl_b32 s8, s67, 1
	v_lshl_add_u64 v[100:101], v[100:101], 0, s[8:9]
	v_lshl_add_u64 v[104:105], v[100:101], 0, v[142:143]
	s_waitcnt lgkmcnt(0)
	v_pk_mul_f32 v[102:103], v[94:95], v[98:99] op_sel_hi:[1,0]
	v_pk_mul_f32 v[100:101], v[92:93], v[98:99] op_sel_hi:[1,0]
	v_pk_mul_f32 v[106:107], v[90:91], v[98:99] op_sel_hi:[1,0]
	v_pk_mul_f32 v[108:109], v[88:89], v[98:99] op_sel_hi:[1,0]
	v_cvt_pk_bf16_f32 v100, v100, v101
	v_cvt_pk_bf16_f32 v101, v102, v103
	s_mov_b64 s[50:51], 0
	v_cvt_pk_bf16_f32 v102, v108, v109
	v_cvt_pk_bf16_f32 v103, v106, v107
	global_store_dwordx4 v[104:105], v[100:103], off offset:-4096
	v_pk_mul_f32 v[106:107], v[82:83], v[98:99] op_sel_hi:[1,0]
	v_pk_mul_f32 v[108:109], v[80:81], v[98:99] op_sel_hi:[1,0]
	v_pk_mul_f32 v[102:103], v[86:87], v[98:99] op_sel_hi:[1,0]
	v_pk_mul_f32 v[100:101], v[84:85], v[98:99] op_sel_hi:[1,0]
	s_nop 0
	v_cvt_pk_bf16_f32 v100, v100, v101
	v_cvt_pk_bf16_f32 v101, v102, v103
	v_cvt_pk_bf16_f32 v102, v108, v109
	v_cvt_pk_bf16_f32 v103, v106, v107
	global_store_dwordx4 v[104:105], v[100:103], off offset:-3840

.LBB0_226:
	s_nop 1
	v_mov_b32_e32 v82, v178
	s_nop 0
	v_or_b32_e32 v80, 48, v152
	s_mov_b64 s[50:51], -1
	s_and_b64 vcc, exec, s[6:7]
	v_ashrrev_i32_e32 v81, 31, v80
	s_cbranch_vccnz .LBB0_228
	v_lshlrev_b64 v[84:85], 11, v[80:81]
	v_lshl_add_u64 v[84:85], s[20:21], 0, v[84:85]
	s_lshl_b32 s8, s0, 9
	v_lshl_add_u64 v[84:85], v[84:85], 0, s[8:9]
	s_lshl_b32 s8, s67, 1
	v_lshl_add_u64 v[84:85], v[84:85], 0, s[8:9]
	v_lshl_add_u64 v[88:89], v[84:85], 0, v[142:143]
	s_waitcnt lgkmcnt(0)
	v_pk_mul_f32 v[86:87], v[78:79], v[82:83] op_sel_hi:[1,0]
	v_pk_mul_f32 v[84:85], v[76:77], v[82:83] op_sel_hi:[1,0]
	v_pk_mul_f32 v[90:91], v[74:75], v[82:83] op_sel_hi:[1,0]
	v_pk_mul_f32 v[92:93], v[72:73], v[82:83] op_sel_hi:[1,0]
	v_cvt_pk_bf16_f32 v84, v84, v85
	v_cvt_pk_bf16_f32 v85, v86, v87
	s_mov_b64 s[50:51], 0
	v_cvt_pk_bf16_f32 v86, v92, v93
	v_cvt_pk_bf16_f32 v87, v90, v91
	global_store_dwordx4 v[88:89], v[84:87], off offset:-4096
	v_pk_mul_f32 v[90:91], v[66:67], v[82:83] op_sel_hi:[1,0]
	v_pk_mul_f32 v[92:93], v[64:65], v[82:83] op_sel_hi:[1,0]
	v_pk_mul_f32 v[86:87], v[70:71], v[82:83] op_sel_hi:[1,0]
	v_pk_mul_f32 v[84:85], v[68:69], v[82:83] op_sel_hi:[1,0]
	s_nop 0
	v_cvt_pk_bf16_f32 v84, v84, v85
	v_cvt_pk_bf16_f32 v85, v86, v87
	v_cvt_pk_bf16_f32 v86, v92, v93
	v_cvt_pk_bf16_f32 v87, v90, v91
	global_store_dwordx4 v[88:89], v[84:87], off offset:-3840

.LBB0_230:
	s_nop 1
	v_mov_b32_e32 v66, v180
	s_nop 0
	v_add_u32_e32 v64, 0x80, v152
	s_mov_b64 s[50:51], -1
	s_and_b64 vcc, exec, s[6:7]
	v_ashrrev_i32_e32 v65, 31, v64
	s_cbranch_vccnz .LBB0_232
	v_lshlrev_b64 v[68:69], 11, v[64:65]
	v_lshl_add_u64 v[68:69], s[20:21], 0, v[68:69]
	s_lshl_b32 s8, s0, 9
	v_lshl_add_u64 v[68:69], v[68:69], 0, s[8:9]
	s_lshl_b32 s8, s67, 1
	v_lshl_add_u64 v[68:69], v[68:69], 0, s[8:9]
	v_lshl_add_u64 v[72:73], v[68:69], 0, v[142:143]
	s_waitcnt lgkmcnt(0)
	v_pk_mul_f32 v[70:71], v[62:63], v[66:67] op_sel_hi:[1,0]
	v_pk_mul_f32 v[68:69], v[60:61], v[66:67] op_sel_hi:[1,0]
	v_pk_mul_f32 v[74:75], v[58:59], v[66:67] op_sel_hi:[1,0]
	v_pk_mul_f32 v[76:77], v[56:57], v[66:67] op_sel_hi:[1,0]
	v_cvt_pk_bf16_f32 v68, v68, v69
	v_cvt_pk_bf16_f32 v69, v70, v71
	s_mov_b64 s[50:51], 0
	v_cvt_pk_bf16_f32 v70, v76, v77
	v_cvt_pk_bf16_f32 v71, v74, v75
	global_store_dwordx4 v[72:73], v[68:71], off offset:-4096
	v_pk_mul_f32 v[74:75], v[50:51], v[66:67] op_sel_hi:[1,0]
	v_pk_mul_f32 v[76:77], v[48:49], v[66:67] op_sel_hi:[1,0]
	v_pk_mul_f32 v[70:71], v[54:55], v[66:67] op_sel_hi:[1,0]
	v_pk_mul_f32 v[68:69], v[52:53], v[66:67] op_sel_hi:[1,0]
	s_nop 0
	v_cvt_pk_bf16_f32 v68, v68, v69
	v_cvt_pk_bf16_f32 v69, v70, v71
	v_cvt_pk_bf16_f32 v70, v76, v77
	v_cvt_pk_bf16_f32 v71, v74, v75
	global_store_dwordx4 v[72:73], v[68:71], off offset:-3840

.LBB0_234:
	s_nop 1
	v_mov_b32_e32 v50, v182
	s_nop 0
	v_add_u32_e32 v48, 0x90, v152
	s_mov_b64 s[50:51], -1
	s_and_b64 vcc, exec, s[6:7]
	v_ashrrev_i32_e32 v49, 31, v48
	s_cbranch_vccnz .LBB0_236
	v_lshlrev_b64 v[52:53], 11, v[48:49]
	v_lshl_add_u64 v[52:53], s[20:21], 0, v[52:53]
	s_lshl_b32 s8, s0, 9
	v_lshl_add_u64 v[52:53], v[52:53], 0, s[8:9]
	s_lshl_b32 s8, s67, 1
	v_lshl_add_u64 v[52:53], v[52:53], 0, s[8:9]
	v_lshl_add_u64 v[56:57], v[52:53], 0, v[142:143]
	s_waitcnt lgkmcnt(0)
	v_pk_mul_f32 v[54:55], v[46:47], v[50:51] op_sel_hi:[1,0]
	v_pk_mul_f32 v[52:53], v[44:45], v[50:51] op_sel_hi:[1,0]
	v_pk_mul_f32 v[58:59], v[42:43], v[50:51] op_sel_hi:[1,0]
	v_pk_mul_f32 v[60:61], v[40:41], v[50:51] op_sel_hi:[1,0]
	v_cvt_pk_bf16_f32 v52, v52, v53
	v_cvt_pk_bf16_f32 v53, v54, v55
	s_mov_b64 s[50:51], 0
	v_cvt_pk_bf16_f32 v54, v60, v61
	v_cvt_pk_bf16_f32 v55, v58, v59
	global_store_dwordx4 v[56:57], v[52:55], off offset:-4096
	v_pk_mul_f32 v[58:59], v[34:35], v[50:51] op_sel_hi:[1,0]
	v_pk_mul_f32 v[60:61], v[32:33], v[50:51] op_sel_hi:[1,0]
	v_pk_mul_f32 v[54:55], v[38:39], v[50:51] op_sel_hi:[1,0]
	v_pk_mul_f32 v[52:53], v[36:37], v[50:51] op_sel_hi:[1,0]
	s_nop 0
	v_cvt_pk_bf16_f32 v52, v52, v53
	v_cvt_pk_bf16_f32 v53, v54, v55
	v_cvt_pk_bf16_f32 v54, v60, v61
	v_cvt_pk_bf16_f32 v55, v58, v59
	global_store_dwordx4 v[56:57], v[52:55], off offset:-3840

.LBB0_238:
	s_nop 1
	v_mov_b32_e32 v34, v184
	s_nop 0
	v_add_u32_e32 v32, 0xa0, v152
	s_mov_b64 s[50:51], -1
	s_and_b64 vcc, exec, s[6:7]
	v_ashrrev_i32_e32 v33, 31, v32
	s_cbranch_vccnz .LBB0_240
	v_lshlrev_b64 v[36:37], 11, v[32:33]
	v_lshl_add_u64 v[36:37], s[20:21], 0, v[36:37]
	s_lshl_b32 s8, s0, 9
	v_lshl_add_u64 v[36:37], v[36:37], 0, s[8:9]
	s_lshl_b32 s8, s67, 1
	v_lshl_add_u64 v[36:37], v[36:37], 0, s[8:9]
	v_lshl_add_u64 v[40:41], v[36:37], 0, v[142:143]
	s_waitcnt lgkmcnt(0)
	v_pk_mul_f32 v[38:39], v[30:31], v[34:35] op_sel_hi:[1,0]
	v_pk_mul_f32 v[36:37], v[28:29], v[34:35] op_sel_hi:[1,0]
	v_pk_mul_f32 v[42:43], v[26:27], v[34:35] op_sel_hi:[1,0]
	v_pk_mul_f32 v[44:45], v[24:25], v[34:35] op_sel_hi:[1,0]
	v_cvt_pk_bf16_f32 v36, v36, v37
	v_cvt_pk_bf16_f32 v37, v38, v39
	s_mov_b64 s[50:51], 0
	v_cvt_pk_bf16_f32 v38, v44, v45
	v_cvt_pk_bf16_f32 v39, v42, v43
	global_store_dwordx4 v[40:41], v[36:39], off offset:-4096
	v_pk_mul_f32 v[42:43], v[18:19], v[34:35] op_sel_hi:[1,0]
	v_pk_mul_f32 v[44:45], v[16:17], v[34:35] op_sel_hi:[1,0]
	v_pk_mul_f32 v[38:39], v[22:23], v[34:35] op_sel_hi:[1,0]
	v_pk_mul_f32 v[36:37], v[20:21], v[34:35] op_sel_hi:[1,0]
	s_nop 0
	v_cvt_pk_bf16_f32 v36, v36, v37
	v_cvt_pk_bf16_f32 v37, v38, v39
	v_cvt_pk_bf16_f32 v38, v44, v45
	v_cvt_pk_bf16_f32 v39, v42, v43
	global_store_dwordx4 v[40:41], v[36:39], off offset:-3840

.LBB0_242:
	s_nop 1
	v_mov_b32_e32 v18, v186
	s_nop 0
	v_add_u32_e32 v16, 0xb0, v152
	s_mov_b64 s[50:51], -1
	s_and_b64 vcc, exec, s[6:7]
	v_ashrrev_i32_e32 v17, 31, v16
	s_cbranch_vccz .LBB0_245
	s_andn2_b64 vcc, exec, s[50:51]
	s_cbranch_vccz .LBB0_246

.LBB0_658:
	s_and_b32 s9, s0, -4
	s_cmp_eq_u32 s9, 4
	s_cselect_b64 s[52:53], -1, 0
	s_lshl_b32 s1, s1, 10
	v_add_u32_e32 v164, s1, v159
	ds_read_b32 v154, v164
	ds_read_b32 v174, v164 offset:64
	ds_read_b32 v176, v164 offset:128
	ds_read_b32 v178, v164 offset:192
	ds_read_b32 v180, v164 offset:512
	ds_read_b32 v182, v164 offset:576
	ds_read_b32 v184, v164 offset:640
	ds_read_b32 v186, v164 offset:704
	v_lshl_or_b32 v150, s0, 8, v158
	v_lshl_add_u32 v148, s8, 8, v131
	v_mov_b64_e32 v[152:153], s[16:17]
	s_cmp_lg_u32 s9, 4
	v_ashrrev_i32_e32 v151, 31, v150
	v_mad_i64_i32 v[152:153], s[8:9], v148, s92, v[152:153]
	v_ashrrev_i32_e32 v149, 31, v148
	v_lshl_add_u64 v[152:153], v[150:151], 1, v[152:153]
	s_waitcnt lgkmcnt(0)
	v_pk_mul_f32 v[126:127], v[126:127], v[154:155] op_sel_hi:[1,0]
	v_pk_mul_f32 v[124:125], v[124:125], v[154:155] op_sel_hi:[1,0]
	v_pk_mul_f32 v[122:123], v[122:123], v[154:155] op_sel_hi:[1,0]
	v_pk_mul_f32 v[120:121], v[120:121], v[154:155] op_sel_hi:[1,0]
	v_cvt_pk_bf16_f32 v166, v124, v125
	v_cvt_pk_bf16_f32 v167, v126, v127
	s_nop 0
	v_cvt_pk_bf16_f32 v168, v120, v121
	v_cvt_pk_bf16_f32 v169, v122, v123
	global_store_dwordx4 v[152:153], v[166:169], off
	s_cbranch_scc1 .LBB0_662
	v_mul_f32_e32 v121, v121, v121
	v_fmac_f32_e32 v121, v120, v120
	v_mul_f32_e32 v120, v123, v123
	v_mul_f32_e32 v125, v125, v125
	v_fmac_f32_e32 v120, v122, v122
	v_and_b32_e32 v122, 64, v163
	v_fmac_f32_e32 v125, v124, v124
	v_mul_f32_e32 v124, v127, v127
	v_add_f32_e32 v120, v121, v120
	v_xor_b32_e32 v121, 16, v163
	v_add_u32_e32 v122, 64, v122
	v_fmac_f32_e32 v124, v126, v126
	v_cmp_lt_i32_e32 vcc, v121, v122
	v_add_f32_e32 v124, v125, v124
	v_add_f32_e32 v120, v124, v120
	v_cndmask_b32_e32 v121, v163, v121, vcc
	v_lshlrev_b32_e32 v121, 2, v121
	ds_bpermute_b32 v121, v121, v120
	s_waitcnt lgkmcnt(0)
	v_add_f32_e32 v120, v120, v121
	v_xor_b32_e32 v121, 32, v163
	v_cmp_lt_i32_e32 vcc, v121, v122
	s_nop 1
	v_cndmask_b32_e32 v121, v163, v121, vcc
	v_lshlrev_b32_e32 v121, 2, v121
	ds_bpermute_b32 v121, v121, v120
	s_and_saveexec_b64 s[8:9], s[4:5]
	s_cbranch_execz .LBB0_661
	s_lshl_b32 s1, s0, 18
	s_add_i32 s10, s1, s85
	s_lshl_b64 s[12:13], s[10:11], 2
	s_add_u32 s12, s81, s12
	s_addc_u32 s13, s82, s13
	s_waitcnt lgkmcnt(0)
	v_add_f32_e32 v122, v120, v121
	v_lshl_add_u64 v[120:121], v[148:149], 2, s[12:13]
	global_store_dword v[120:121], v122, off

.LBB0_666:
	s_nop 1
	v_mov_b32_e32 v114, v174
	v_or_b32_e32 v115, 16, v148
	s_waitcnt lgkmcnt(0)
	v_mov_b64_e32 v[112:113], s[16:17]
	v_mad_i64_i32 v[112:113], s[12:13], v115, s92, v[112:113]
	v_lshl_add_u64 v[112:113], v[150:151], 1, v[112:113]
	v_pk_mul_f32 v[110:111], v[110:111], v[114:115] op_sel_hi:[1,0]
	v_pk_mul_f32 v[108:109], v[108:109], v[114:115] op_sel_hi:[1,0]
	v_pk_mul_f32 v[106:107], v[106:107], v[114:115] op_sel_hi:[1,0]
	v_pk_mul_f32 v[104:105], v[104:105], v[114:115] op_sel_hi:[1,0]
	s_and_b64 vcc, exec, s[8:9]
	v_cvt_pk_bf16_f32 v116, v108, v109
	v_cvt_pk_bf16_f32 v117, v110, v111
	v_cvt_pk_bf16_f32 v118, v104, v105
	v_cvt_pk_bf16_f32 v119, v106, v107
	global_store_dwordx4 v[112:113], v[116:119], off
	s_cbranch_vccnz .LBB0_670
	v_mul_f32_e32 v105, v105, v105
	v_fmac_f32_e32 v105, v104, v104
	v_mul_f32_e32 v104, v107, v107
	v_mul_f32_e32 v109, v109, v109
	v_fmac_f32_e32 v104, v106, v106
	v_and_b32_e32 v106, 64, v163
	v_fmac_f32_e32 v109, v108, v108
	v_mul_f32_e32 v108, v111, v111
	v_add_f32_e32 v104, v105, v104
	v_xor_b32_e32 v105, 16, v163
	v_add_u32_e32 v106, 64, v106
	v_fmac_f32_e32 v108, v110, v110
	v_cmp_lt_i32_e32 vcc, v105, v106
	v_add_f32_e32 v108, v109, v108
	v_add_f32_e32 v104, v108, v104
	v_cndmask_b32_e32 v105, v163, v105, vcc
	v_lshlrev_b32_e32 v105, 2, v105
	ds_bpermute_b32 v105, v105, v104
	s_waitcnt lgkmcnt(0)
	v_add_f32_e32 v104, v104, v105
	v_xor_b32_e32 v105, 32, v163
	v_cmp_lt_i32_e32 vcc, v105, v106
	s_nop 1
	v_cndmask_b32_e32 v105, v163, v105, vcc
	v_lshlrev_b32_e32 v105, 2, v105
	ds_bpermute_b32 v105, v105, v104
	s_and_saveexec_b64 s[52:53], s[4:5]
	s_cbranch_execz .LBB0_669
	s_lshl_b32 s1, s0, 18
	s_add_i32 s10, s1, s85
	s_lshl_b64 s[12:13], s[10:11], 2
	s_add_u32 s12, s81, s12
	s_addc_u32 s13, s82, s13
	s_waitcnt lgkmcnt(0)
	v_add_f32_e32 v106, v104, v105
	v_lshl_add_u64 v[104:105], v[148:149], 2, s[12:13]
	global_store_dword v[104:105], v106, off offset:64

.LBB0_674:
	s_nop 1
	v_mov_b32_e32 v98, v176
	v_or_b32_e32 v99, 32, v148
	s_waitcnt lgkmcnt(0)
	v_mov_b64_e32 v[96:97], s[16:17]
	v_mad_i64_i32 v[96:97], s[12:13], v99, s92, v[96:97]
	v_lshl_add_u64 v[96:97], v[150:151], 1, v[96:97]
	v_pk_mul_f32 v[94:95], v[94:95], v[98:99] op_sel_hi:[1,0]
	v_pk_mul_f32 v[92:93], v[92:93], v[98:99] op_sel_hi:[1,0]
	v_pk_mul_f32 v[90:91], v[90:91], v[98:99] op_sel_hi:[1,0]
	v_pk_mul_f32 v[88:89], v[88:89], v[98:99] op_sel_hi:[1,0]
	s_and_b64 vcc, exec, s[8:9]
	v_cvt_pk_bf16_f32 v100, v92, v93
	v_cvt_pk_bf16_f32 v101, v94, v95
	v_cvt_pk_bf16_f32 v102, v88, v89
	v_cvt_pk_bf16_f32 v103, v90, v91
	global_store_dwordx4 v[96:97], v[100:103], off
	s_cbranch_vccnz .LBB0_678
	v_mul_f32_e32 v89, v89, v89
	v_fmac_f32_e32 v89, v88, v88
	v_mul_f32_e32 v88, v91, v91
	v_mul_f32_e32 v93, v93, v93
	v_fmac_f32_e32 v88, v90, v90
	v_and_b32_e32 v90, 64, v163
	v_fmac_f32_e32 v93, v92, v92
	v_mul_f32_e32 v92, v95, v95
	v_add_f32_e32 v88, v89, v88
	v_xor_b32_e32 v89, 16, v163
	v_add_u32_e32 v90, 64, v90
	v_fmac_f32_e32 v92, v94, v94
	v_cmp_lt_i32_e32 vcc, v89, v90
	v_add_f32_e32 v92, v93, v92
	v_add_f32_e32 v88, v92, v88
	v_cndmask_b32_e32 v89, v163, v89, vcc
	v_lshlrev_b32_e32 v89, 2, v89
	ds_bpermute_b32 v89, v89, v88
	s_waitcnt lgkmcnt(0)
	v_add_f32_e32 v88, v88, v89
	v_xor_b32_e32 v89, 32, v163
	v_cmp_lt_i32_e32 vcc, v89, v90
	s_nop 1
	v_cndmask_b32_e32 v89, v163, v89, vcc
	v_lshlrev_b32_e32 v89, 2, v89
	ds_bpermute_b32 v89, v89, v88
	s_and_saveexec_b64 s[52:53], s[4:5]
	s_cbranch_execz .LBB0_677
	s_lshl_b32 s1, s0, 18
	s_add_i32 s10, s1, s85
	s_lshl_b64 s[12:13], s[10:11], 2
	s_add_u32 s12, s81, s12
	s_addc_u32 s13, s82, s13
	s_waitcnt lgkmcnt(0)
	v_add_f32_e32 v90, v88, v89
	v_lshl_add_u64 v[88:89], v[148:149], 2, s[12:13]
	global_store_dword v[88:89], v90, off offset:128

.LBB0_682:
	s_nop 1
	v_mov_b32_e32 v82, v178
	v_or_b32_e32 v83, 48, v148
	s_waitcnt lgkmcnt(0)
	v_mov_b64_e32 v[80:81], s[16:17]
	v_mad_i64_i32 v[80:81], s[12:13], v83, s92, v[80:81]
	v_lshl_add_u64 v[80:81], v[150:151], 1, v[80:81]
	v_pk_mul_f32 v[78:79], v[78:79], v[82:83] op_sel_hi:[1,0]
	v_pk_mul_f32 v[76:77], v[76:77], v[82:83] op_sel_hi:[1,0]
	v_pk_mul_f32 v[74:75], v[74:75], v[82:83] op_sel_hi:[1,0]
	v_pk_mul_f32 v[72:73], v[72:73], v[82:83] op_sel_hi:[1,0]
	s_and_b64 vcc, exec, s[8:9]
	v_cvt_pk_bf16_f32 v84, v76, v77
	v_cvt_pk_bf16_f32 v85, v78, v79
	v_cvt_pk_bf16_f32 v86, v72, v73
	v_cvt_pk_bf16_f32 v87, v74, v75
	global_store_dwordx4 v[80:81], v[84:87], off
	s_cbranch_vccnz .LBB0_686
	v_mul_f32_e32 v73, v73, v73
	v_fmac_f32_e32 v73, v72, v72
	v_mul_f32_e32 v72, v75, v75
	v_mul_f32_e32 v77, v77, v77
	v_fmac_f32_e32 v72, v74, v74
	v_and_b32_e32 v74, 64, v163
	v_fmac_f32_e32 v77, v76, v76
	v_mul_f32_e32 v76, v79, v79
	v_add_f32_e32 v72, v73, v72
	v_xor_b32_e32 v73, 16, v163
	v_add_u32_e32 v74, 64, v74
	v_fmac_f32_e32 v76, v78, v78
	v_cmp_lt_i32_e32 vcc, v73, v74
	v_add_f32_e32 v76, v77, v76
	v_add_f32_e32 v72, v76, v72
	v_cndmask_b32_e32 v73, v163, v73, vcc
	v_lshlrev_b32_e32 v73, 2, v73
	ds_bpermute_b32 v73, v73, v72
	s_waitcnt lgkmcnt(0)
	v_add_f32_e32 v72, v72, v73
	v_xor_b32_e32 v73, 32, v163
	v_cmp_lt_i32_e32 vcc, v73, v74
	s_nop 1
	v_cndmask_b32_e32 v73, v163, v73, vcc
	v_lshlrev_b32_e32 v73, 2, v73
	ds_bpermute_b32 v73, v73, v72
	s_and_saveexec_b64 s[52:53], s[4:5]
	s_cbranch_execz .LBB0_685
	s_lshl_b32 s1, s0, 18
	s_add_i32 s10, s1, s85
	s_lshl_b64 s[12:13], s[10:11], 2
	s_add_u32 s12, s81, s12
	s_addc_u32 s13, s82, s13
	s_waitcnt lgkmcnt(0)
	v_add_f32_e32 v74, v72, v73
	v_lshl_add_u64 v[72:73], v[148:149], 2, s[12:13]
	global_store_dword v[72:73], v74, off offset:192

.LBB0_690:
	s_nop 1
	v_mov_b32_e32 v66, v180
	v_add_u32_e32 v67, 0x80, v148
	s_waitcnt lgkmcnt(0)
	v_mov_b64_e32 v[64:65], s[16:17]
	v_mad_i64_i32 v[64:65], s[12:13], v67, s92, v[64:65]
	v_lshl_add_u64 v[64:65], v[150:151], 1, v[64:65]
	v_pk_mul_f32 v[62:63], v[62:63], v[66:67] op_sel_hi:[1,0]
	v_pk_mul_f32 v[60:61], v[60:61], v[66:67] op_sel_hi:[1,0]
	v_pk_mul_f32 v[58:59], v[58:59], v[66:67] op_sel_hi:[1,0]
	v_pk_mul_f32 v[56:57], v[56:57], v[66:67] op_sel_hi:[1,0]
	s_and_b64 vcc, exec, s[8:9]
	v_cvt_pk_bf16_f32 v68, v60, v61
	v_cvt_pk_bf16_f32 v69, v62, v63
	v_cvt_pk_bf16_f32 v70, v56, v57
	v_cvt_pk_bf16_f32 v71, v58, v59
	global_store_dwordx4 v[64:65], v[68:71], off
	s_cbranch_vccnz .LBB0_694
	v_mul_f32_e32 v57, v57, v57
	v_fmac_f32_e32 v57, v56, v56
	v_mul_f32_e32 v56, v59, v59
	v_mul_f32_e32 v61, v61, v61
	v_fmac_f32_e32 v56, v58, v58
	v_and_b32_e32 v58, 64, v163
	v_fmac_f32_e32 v61, v60, v60
	v_mul_f32_e32 v60, v63, v63
	v_add_f32_e32 v56, v57, v56
	v_xor_b32_e32 v57, 16, v163
	v_add_u32_e32 v58, 64, v58
	v_fmac_f32_e32 v60, v62, v62
	v_cmp_lt_i32_e32 vcc, v57, v58
	v_add_f32_e32 v60, v61, v60
	v_add_f32_e32 v56, v60, v56
	v_cndmask_b32_e32 v57, v163, v57, vcc
	v_lshlrev_b32_e32 v57, 2, v57
	ds_bpermute_b32 v57, v57, v56
	s_waitcnt lgkmcnt(0)
	v_add_f32_e32 v56, v56, v57
	v_xor_b32_e32 v57, 32, v163
	v_cmp_lt_i32_e32 vcc, v57, v58
	s_nop 1
	v_cndmask_b32_e32 v57, v163, v57, vcc
	v_lshlrev_b32_e32 v57, 2, v57
	ds_bpermute_b32 v57, v57, v56
	s_and_saveexec_b64 s[52:53], s[4:5]
	s_cbranch_execz .LBB0_693
	s_lshl_b32 s1, s0, 18
	s_add_i32 s10, s1, s85
	s_lshl_b64 s[12:13], s[10:11], 2
	s_add_u32 s12, s81, s12
	s_addc_u32 s13, s82, s13
	s_waitcnt lgkmcnt(0)
	v_add_f32_e32 v58, v56, v57
	v_lshl_add_u64 v[56:57], v[148:149], 2, s[12:13]
	global_store_dword v[56:57], v58, off offset:512

.LBB0_698:
	s_nop 1
	v_mov_b32_e32 v50, v182
	v_add_u32_e32 v51, 0x90, v148
	s_waitcnt lgkmcnt(0)
	v_mov_b64_e32 v[48:49], s[16:17]
	v_mad_i64_i32 v[48:49], s[12:13], v51, s92, v[48:49]
	v_lshl_add_u64 v[48:49], v[150:151], 1, v[48:49]
	v_pk_mul_f32 v[46:47], v[46:47], v[50:51] op_sel_hi:[1,0]
	v_pk_mul_f32 v[44:45], v[44:45], v[50:51] op_sel_hi:[1,0]
	v_pk_mul_f32 v[42:43], v[42:43], v[50:51] op_sel_hi:[1,0]
	v_pk_mul_f32 v[40:41], v[40:41], v[50:51] op_sel_hi:[1,0]
	s_and_b64 vcc, exec, s[8:9]
	v_cvt_pk_bf16_f32 v52, v44, v45
	v_cvt_pk_bf16_f32 v53, v46, v47
	v_cvt_pk_bf16_f32 v54, v40, v41
	v_cvt_pk_bf16_f32 v55, v42, v43
	global_store_dwordx4 v[48:49], v[52:55], off
	s_cbranch_vccnz .LBB0_702
	v_mul_f32_e32 v41, v41, v41
	v_fmac_f32_e32 v41, v40, v40
	v_mul_f32_e32 v40, v43, v43
	v_mul_f32_e32 v45, v45, v45
	v_fmac_f32_e32 v40, v42, v42
	v_and_b32_e32 v42, 64, v163
	v_fmac_f32_e32 v45, v44, v44
	v_mul_f32_e32 v44, v47, v47
	v_add_f32_e32 v40, v41, v40
	v_xor_b32_e32 v41, 16, v163
	v_add_u32_e32 v42, 64, v42
	v_fmac_f32_e32 v44, v46, v46
	v_cmp_lt_i32_e32 vcc, v41, v42
	v_add_f32_e32 v44, v45, v44
	v_add_f32_e32 v40, v44, v40
	v_cndmask_b32_e32 v41, v163, v41, vcc
	v_lshlrev_b32_e32 v41, 2, v41
	ds_bpermute_b32 v41, v41, v40
	s_waitcnt lgkmcnt(0)
	v_add_f32_e32 v40, v40, v41
	v_xor_b32_e32 v41, 32, v163
	v_cmp_lt_i32_e32 vcc, v41, v42
	s_nop 1
	v_cndmask_b32_e32 v41, v163, v41, vcc
	v_lshlrev_b32_e32 v41, 2, v41
	ds_bpermute_b32 v41, v41, v40
	s_and_saveexec_b64 s[52:53], s[4:5]
	s_cbranch_execz .LBB0_701
	s_lshl_b32 s1, s0, 18
	s_add_i32 s10, s1, s85
	s_lshl_b64 s[12:13], s[10:11], 2
	s_add_u32 s12, s81, s12
	s_addc_u32 s13, s82, s13
	s_waitcnt lgkmcnt(0)
	v_add_f32_e32 v42, v40, v41
	v_lshl_add_u64 v[40:41], v[148:149], 2, s[12:13]
	global_store_dword v[40:41], v42, off offset:576

.LBB0_706:
	s_nop 1
	v_mov_b32_e32 v34, v184
	v_add_u32_e32 v35, 0xa0, v148
	s_waitcnt lgkmcnt(0)
	v_mov_b64_e32 v[32:33], s[16:17]
	v_mad_i64_i32 v[32:33], s[12:13], v35, s92, v[32:33]
	v_lshl_add_u64 v[32:33], v[150:151], 1, v[32:33]
	v_pk_mul_f32 v[30:31], v[30:31], v[34:35] op_sel_hi:[1,0]
	v_pk_mul_f32 v[28:29], v[28:29], v[34:35] op_sel_hi:[1,0]
	v_pk_mul_f32 v[26:27], v[26:27], v[34:35] op_sel_hi:[1,0]
	v_pk_mul_f32 v[24:25], v[24:25], v[34:35] op_sel_hi:[1,0]
	s_and_b64 vcc, exec, s[8:9]
	v_cvt_pk_bf16_f32 v36, v28, v29
	v_cvt_pk_bf16_f32 v37, v30, v31
	v_cvt_pk_bf16_f32 v38, v24, v25
	v_cvt_pk_bf16_f32 v39, v26, v27
	global_store_dwordx4 v[32:33], v[36:39], off
	s_cbranch_vccnz .LBB0_710
	v_mul_f32_e32 v25, v25, v25
	v_fmac_f32_e32 v25, v24, v24
	v_mul_f32_e32 v24, v27, v27
	v_mul_f32_e32 v29, v29, v29
	v_fmac_f32_e32 v24, v26, v26
	v_and_b32_e32 v26, 64, v163
	v_fmac_f32_e32 v29, v28, v28
	v_mul_f32_e32 v28, v31, v31
	v_add_f32_e32 v24, v25, v24
	v_xor_b32_e32 v25, 16, v163
	v_add_u32_e32 v26, 64, v26
	v_fmac_f32_e32 v28, v30, v30
	v_cmp_lt_i32_e32 vcc, v25, v26
	v_add_f32_e32 v28, v29, v28
	v_add_f32_e32 v24, v28, v24
	v_cndmask_b32_e32 v25, v163, v25, vcc
	v_lshlrev_b32_e32 v25, 2, v25
	ds_bpermute_b32 v25, v25, v24
	s_waitcnt lgkmcnt(0)
	v_add_f32_e32 v24, v24, v25
	v_xor_b32_e32 v25, 32, v163
	v_cmp_lt_i32_e32 vcc, v25, v26
	s_nop 1
	v_cndmask_b32_e32 v25, v163, v25, vcc
	v_lshlrev_b32_e32 v25, 2, v25
	ds_bpermute_b32 v25, v25, v24
	s_and_saveexec_b64 s[52:53], s[4:5]
	s_cbranch_execz .LBB0_709
	s_lshl_b32 s1, s0, 18
	s_add_i32 s10, s1, s85
	s_lshl_b64 s[12:13], s[10:11], 2
	s_add_u32 s12, s81, s12
	s_addc_u32 s13, s82, s13
	s_waitcnt lgkmcnt(0)
	v_add_f32_e32 v26, v24, v25
	v_lshl_add_u64 v[24:25], v[148:149], 2, s[12:13]
	global_store_dword v[24:25], v26, off offset:640

.LBB0_714:
	s_nop 1
	v_mov_b32_e32 v18, v186
	v_add_u32_e32 v19, 0xb0, v148
	s_waitcnt lgkmcnt(0)
	v_mov_b64_e32 v[16:17], s[16:17]
	v_mad_i64_i32 v[16:17], s[12:13], v19, s92, v[16:17]
	v_lshl_add_u64 v[16:17], v[150:151], 1, v[16:17]
	v_pk_mul_f32 v[14:15], v[14:15], v[18:19] op_sel_hi:[1,0]
	v_pk_mul_f32 v[12:13], v[12:13], v[18:19] op_sel_hi:[1,0]
	v_pk_mul_f32 v[10:11], v[10:11], v[18:19] op_sel_hi:[1,0]
	v_pk_mul_f32 v[8:9], v[8:9], v[18:19] op_sel_hi:[1,0]
	s_and_b64 vcc, exec, s[8:9]
	v_cvt_pk_bf16_f32 v20, v12, v13
	v_cvt_pk_bf16_f32 v21, v14, v15
	v_cvt_pk_bf16_f32 v22, v8, v9
	v_cvt_pk_bf16_f32 v23, v10, v11
	global_store_dwordx4 v[16:17], v[20:23], off
	s_cbranch_vccnz .LBB0_718
	v_mul_f32_e32 v9, v9, v9
	v_fmac_f32_e32 v9, v8, v8
	v_mul_f32_e32 v8, v11, v11
	v_mul_f32_e32 v13, v13, v13
	v_fmac_f32_e32 v8, v10, v10
	v_and_b32_e32 v10, 64, v163
	v_fmac_f32_e32 v13, v12, v12
	v_mul_f32_e32 v12, v15, v15
	v_add_f32_e32 v8, v9, v8
	v_xor_b32_e32 v9, 16, v163
	v_add_u32_e32 v10, 64, v10
	v_fmac_f32_e32 v12, v14, v14
	v_cmp_lt_i32_e32 vcc, v9, v10
	v_add_f32_e32 v12, v13, v12
	v_add_f32_e32 v8, v12, v8
	v_cndmask_b32_e32 v9, v163, v9, vcc
	v_lshlrev_b32_e32 v9, 2, v9
	ds_bpermute_b32 v9, v9, v8
	s_waitcnt lgkmcnt(0)
	v_add_f32_e32 v8, v8, v9
	v_xor_b32_e32 v9, 32, v163
	v_cmp_lt_i32_e32 vcc, v9, v10
	s_nop 1
	v_cndmask_b32_e32 v9, v163, v9, vcc
	v_lshlrev_b32_e32 v9, 2, v9
	ds_bpermute_b32 v9, v9, v8
	s_and_saveexec_b64 s[52:53], s[4:5]
	s_cbranch_execz .LBB0_717
	s_lshl_b32 s1, s0, 18
	s_add_i32 s10, s1, s85
	s_lshl_b64 s[12:13], s[10:11], 2
	s_add_u32 s12, s81, s12
	s_addc_u32 s13, s82, s13
	s_waitcnt lgkmcnt(0)
	v_add_f32_e32 v10, v8, v9
	v_lshl_add_u64 v[8:9], v[148:149], 2, s[12:13]
	global_store_dword v[8:9], v10, off offset:704

.LBB0_1238:
	v_lshl_add_u32 v161, s62, 10, v153
	ds_read_b32 v160, v161
	ds_read_b32 v174, v161 offset:64
	ds_read_b32 v176, v161 offset:128
	ds_read_b32 v178, v161 offset:192
	ds_read_b32 v180, v161 offset:512
	ds_read_b32 v182, v161 offset:576
	ds_read_b32 v184, v161 offset:640
	ds_read_b32 v186, v161 offset:704
	v_lshl_or_b32 v150, s63, 8, v154
	v_lshl_add_u32 v159, s30, 8, v131
	v_ashrrev_i32_e32 v151, 31, v150
	v_mov_b64_e32 v[148:149], s[16:17]
	v_mad_i64_i32 v[162:163], s[34:35], v159, s57, v[148:149]
	v_lshlrev_b64 v[150:151], 1, v[150:151]
	v_lshl_add_u64 v[162:163], v[162:163], 0, v[150:151]
	s_waitcnt lgkmcnt(0)
	v_pk_mul_f32 v[126:127], v[126:127], v[160:161] op_sel_hi:[1,0]
	v_pk_mul_f32 v[124:125], v[124:125], v[160:161] op_sel_hi:[1,0]
	v_pk_mul_f32 v[164:165], v[122:123], v[160:161] op_sel_hi:[1,0]
	v_pk_mul_f32 v[122:123], v[120:121], v[160:161] op_sel_hi:[1,0]
	v_cvt_pk_bf16_f32 v120, v124, v125
	v_cvt_pk_bf16_f32 v121, v126, v127
	v_pk_mul_f32 v[116:117], v[116:117], v[160:161] op_sel_hi:[1,0]
	v_cvt_pk_bf16_f32 v122, v122, v123
	v_cvt_pk_bf16_f32 v123, v164, v165
	global_store_dwordx4 v[162:163], v[120:123], off
	v_pk_mul_f32 v[118:119], v[118:119], v[160:161] op_sel_hi:[1,0]
	s_andn2_b64 vcc, exec, s[4:5]
	v_pk_mul_f32 v[120:121], v[114:115], v[160:161] op_sel_hi:[1,0]
	v_pk_mul_f32 v[114:115], v[112:113], v[160:161] op_sel_hi:[1,0]
	v_cvt_pk_bf16_f32 v112, v116, v117
	v_cvt_pk_bf16_f32 v113, v118, v119
	s_mov_b64 s[4:5], -1
	v_cvt_pk_bf16_f32 v114, v114, v115
	v_cvt_pk_bf16_f32 v115, v120, v121
	global_store_dwordx4 v[162:163], v[112:115], off offset:256
	s_nop 1
	v_mov_b32_e32 v112, v174
	s_nop 0
	v_or_b32_e32 v113, 16, v159
	v_mad_i64_i32 v[114:115], s[34:35], v113, s57, v[148:149]
	v_lshl_add_u64 v[114:115], v[114:115], 0, v[150:151]
	s_waitcnt lgkmcnt(0)
	v_pk_mul_f32 v[110:111], v[110:111], v[112:113] op_sel_hi:[1,0]
	v_pk_mul_f32 v[108:109], v[108:109], v[112:113] op_sel_hi:[1,0]
	v_pk_mul_f32 v[116:117], v[106:107], v[112:113] op_sel_hi:[1,0]
	v_pk_mul_f32 v[106:107], v[104:105], v[112:113] op_sel_hi:[1,0]
	v_cvt_pk_bf16_f32 v104, v108, v109
	v_cvt_pk_bf16_f32 v105, v110, v111
	v_pk_mul_f32 v[100:101], v[100:101], v[112:113] op_sel_hi:[1,0]
	v_cvt_pk_bf16_f32 v106, v106, v107
	v_cvt_pk_bf16_f32 v107, v116, v117
	global_store_dwordx4 v[114:115], v[104:107], off
	v_pk_mul_f32 v[102:103], v[102:103], v[112:113] op_sel_hi:[1,0]
	s_nop 0
	v_pk_mul_f32 v[104:105], v[98:99], v[112:113] op_sel_hi:[1,0]
	v_pk_mul_f32 v[98:99], v[96:97], v[112:113] op_sel_hi:[1,0]
	v_cvt_pk_bf16_f32 v96, v100, v101
	v_cvt_pk_bf16_f32 v97, v102, v103
	s_nop 0
	v_cvt_pk_bf16_f32 v98, v98, v99
	v_cvt_pk_bf16_f32 v99, v104, v105
	global_store_dwordx4 v[114:115], v[96:99], off offset:256
	s_nop 1
	v_mov_b32_e32 v96, v176
	s_nop 0
	v_or_b32_e32 v97, 32, v159
	v_mad_i64_i32 v[98:99], s[34:35], v97, s57, v[148:149]
	v_lshl_add_u64 v[98:99], v[98:99], 0, v[150:151]
	s_waitcnt lgkmcnt(0)
	v_pk_mul_f32 v[94:95], v[94:95], v[96:97] op_sel_hi:[1,0]
	v_pk_mul_f32 v[92:93], v[92:93], v[96:97] op_sel_hi:[1,0]
	v_pk_mul_f32 v[100:101], v[90:91], v[96:97] op_sel_hi:[1,0]
	v_pk_mul_f32 v[90:91], v[88:89], v[96:97] op_sel_hi:[1,0]
	v_cvt_pk_bf16_f32 v88, v92, v93
	v_cvt_pk_bf16_f32 v89, v94, v95
	v_pk_mul_f32 v[84:85], v[84:85], v[96:97] op_sel_hi:[1,0]
	v_cvt_pk_bf16_f32 v90, v90, v91
	v_cvt_pk_bf16_f32 v91, v100, v101
	global_store_dwordx4 v[98:99], v[88:91], off
	v_pk_mul_f32 v[86:87], v[86:87], v[96:97] op_sel_hi:[1,0]
	s_nop 0
	v_pk_mul_f32 v[88:89], v[82:83], v[96:97] op_sel_hi:[1,0]
	v_pk_mul_f32 v[82:83], v[80:81], v[96:97] op_sel_hi:[1,0]
	v_cvt_pk_bf16_f32 v80, v84, v85
	v_cvt_pk_bf16_f32 v81, v86, v87
	s_nop 0
	v_cvt_pk_bf16_f32 v82, v82, v83
	v_cvt_pk_bf16_f32 v83, v88, v89
	global_store_dwordx4 v[98:99], v[80:83], off offset:256
	s_nop 1
	v_mov_b32_e32 v80, v178
	s_nop 0
	v_or_b32_e32 v81, 48, v159
	v_mad_i64_i32 v[82:83], s[34:35], v81, s57, v[148:149]
	v_lshl_add_u64 v[82:83], v[82:83], 0, v[150:151]
	s_waitcnt lgkmcnt(0)
	v_pk_mul_f32 v[78:79], v[78:79], v[80:81] op_sel_hi:[1,0]
	v_pk_mul_f32 v[76:77], v[76:77], v[80:81] op_sel_hi:[1,0]
	v_pk_mul_f32 v[84:85], v[74:75], v[80:81] op_sel_hi:[1,0]
	v_pk_mul_f32 v[74:75], v[72:73], v[80:81] op_sel_hi:[1,0]
	v_cvt_pk_bf16_f32 v72, v76, v77
	v_cvt_pk_bf16_f32 v73, v78, v79
	v_pk_mul_f32 v[68:69], v[68:69], v[80:81] op_sel_hi:[1,0]
	v_cvt_pk_bf16_f32 v74, v74, v75
	v_cvt_pk_bf16_f32 v75, v84, v85
	global_store_dwordx4 v[82:83], v[72:75], off
	v_pk_mul_f32 v[70:71], v[70:71], v[80:81] op_sel_hi:[1,0]
	s_nop 0
	v_pk_mul_f32 v[72:73], v[66:67], v[80:81] op_sel_hi:[1,0]
	v_pk_mul_f32 v[66:67], v[64:65], v[80:81] op_sel_hi:[1,0]
	v_cvt_pk_bf16_f32 v64, v68, v69
	v_cvt_pk_bf16_f32 v65, v70, v71
	s_nop 0
	v_cvt_pk_bf16_f32 v66, v66, v67
	v_cvt_pk_bf16_f32 v67, v72, v73
	global_store_dwordx4 v[82:83], v[64:67], off offset:256
	s_nop 1
	v_mov_b32_e32 v64, v180
	s_nop 0
	v_add_u32_e32 v65, 0x80, v159
	v_mad_i64_i32 v[66:67], s[34:35], v65, s57, v[148:149]
	v_lshl_add_u64 v[66:67], v[66:67], 0, v[150:151]
	s_waitcnt lgkmcnt(0)
	v_pk_mul_f32 v[62:63], v[62:63], v[64:65] op_sel_hi:[1,0]
	v_pk_mul_f32 v[60:61], v[60:61], v[64:65] op_sel_hi:[1,0]
	v_pk_mul_f32 v[68:69], v[58:59], v[64:65] op_sel_hi:[1,0]
	v_pk_mul_f32 v[58:59], v[56:57], v[64:65] op_sel_hi:[1,0]
	v_cvt_pk_bf16_f32 v56, v60, v61
	v_cvt_pk_bf16_f32 v57, v62, v63
	v_pk_mul_f32 v[52:53], v[52:53], v[64:65] op_sel_hi:[1,0]
	v_cvt_pk_bf16_f32 v58, v58, v59
	v_cvt_pk_bf16_f32 v59, v68, v69
	global_store_dwordx4 v[66:67], v[56:59], off
	v_pk_mul_f32 v[54:55], v[54:55], v[64:65] op_sel_hi:[1,0]
	s_nop 0
	v_pk_mul_f32 v[56:57], v[50:51], v[64:65] op_sel_hi:[1,0]
	v_pk_mul_f32 v[50:51], v[48:49], v[64:65] op_sel_hi:[1,0]
	v_cvt_pk_bf16_f32 v48, v52, v53
	v_cvt_pk_bf16_f32 v49, v54, v55
	s_nop 0
	v_cvt_pk_bf16_f32 v50, v50, v51
	v_cvt_pk_bf16_f32 v51, v56, v57
	global_store_dwordx4 v[66:67], v[48:51], off offset:256
	s_nop 1
	v_mov_b32_e32 v48, v182
	s_nop 0
	v_add_u32_e32 v49, 0x90, v159
	v_mad_i64_i32 v[50:51], s[34:35], v49, s57, v[148:149]
	v_lshl_add_u64 v[50:51], v[50:51], 0, v[150:151]
	s_waitcnt lgkmcnt(0)
	v_pk_mul_f32 v[46:47], v[46:47], v[48:49] op_sel_hi:[1,0]
	v_pk_mul_f32 v[44:45], v[44:45], v[48:49] op_sel_hi:[1,0]
	v_pk_mul_f32 v[52:53], v[42:43], v[48:49] op_sel_hi:[1,0]
	v_pk_mul_f32 v[42:43], v[40:41], v[48:49] op_sel_hi:[1,0]
	v_cvt_pk_bf16_f32 v40, v44, v45
	v_cvt_pk_bf16_f32 v41, v46, v47
	v_pk_mul_f32 v[36:37], v[36:37], v[48:49] op_sel_hi:[1,0]
	v_cvt_pk_bf16_f32 v42, v42, v43
	v_cvt_pk_bf16_f32 v43, v52, v53
	global_store_dwordx4 v[50:51], v[40:43], off
	v_pk_mul_f32 v[38:39], v[38:39], v[48:49] op_sel_hi:[1,0]
	s_nop 0
	v_pk_mul_f32 v[40:41], v[34:35], v[48:49] op_sel_hi:[1,0]
	v_pk_mul_f32 v[34:35], v[32:33], v[48:49] op_sel_hi:[1,0]
	v_cvt_pk_bf16_f32 v32, v36, v37
	v_cvt_pk_bf16_f32 v33, v38, v39
	s_nop 0
	v_cvt_pk_bf16_f32 v34, v34, v35
	v_cvt_pk_bf16_f32 v35, v40, v41
	global_store_dwordx4 v[50:51], v[32:35], off offset:256
	s_nop 1
	v_mov_b32_e32 v32, v184
	s_nop 0
	v_add_u32_e32 v33, 0xa0, v159
	v_mad_i64_i32 v[34:35], s[34:35], v33, s57, v[148:149]
	v_lshl_add_u64 v[34:35], v[34:35], 0, v[150:151]
	s_waitcnt lgkmcnt(0)
	v_pk_mul_f32 v[30:31], v[30:31], v[32:33] op_sel_hi:[1,0]
	v_pk_mul_f32 v[28:29], v[28:29], v[32:33] op_sel_hi:[1,0]
	v_pk_mul_f32 v[36:37], v[26:27], v[32:33] op_sel_hi:[1,0]
	v_pk_mul_f32 v[26:27], v[24:25], v[32:33] op_sel_hi:[1,0]
	v_cvt_pk_bf16_f32 v24, v28, v29
	v_cvt_pk_bf16_f32 v25, v30, v31
	v_pk_mul_f32 v[20:21], v[20:21], v[32:33] op_sel_hi:[1,0]
	v_cvt_pk_bf16_f32 v26, v26, v27
	v_cvt_pk_bf16_f32 v27, v36, v37
	global_store_dwordx4 v[34:35], v[24:27], off
	v_pk_mul_f32 v[22:23], v[22:23], v[32:33] op_sel_hi:[1,0]
	s_nop 0
	v_pk_mul_f32 v[24:25], v[18:19], v[32:33] op_sel_hi:[1,0]
	v_pk_mul_f32 v[18:19], v[16:17], v[32:33] op_sel_hi:[1,0]
	v_cvt_pk_bf16_f32 v16, v20, v21
	v_cvt_pk_bf16_f32 v17, v22, v23
	s_nop 0
	v_cvt_pk_bf16_f32 v18, v18, v19
	v_cvt_pk_bf16_f32 v19, v24, v25
	global_store_dwordx4 v[34:35], v[16:19], off offset:256
	s_nop 1
	v_mov_b32_e32 v16, v186
	s_nop 0
	v_add_u32_e32 v17, 0xb0, v159
	v_mad_i64_i32 v[18:19], s[34:35], v17, s57, v[148:149]
	v_lshl_add_u64 v[18:19], v[18:19], 0, v[150:151]
	s_waitcnt lgkmcnt(0)
	v_pk_mul_f32 v[14:15], v[14:15], v[16:17] op_sel_hi:[1,0]
	v_pk_mul_f32 v[12:13], v[12:13], v[16:17] op_sel_hi:[1,0]
	v_pk_mul_f32 v[20:21], v[10:11], v[16:17] op_sel_hi:[1,0]
	v_pk_mul_f32 v[10:11], v[8:9], v[16:17] op_sel_hi:[1,0]
	v_cvt_pk_bf16_f32 v8, v12, v13
	v_cvt_pk_bf16_f32 v9, v14, v15
	v_pk_mul_f32 v[6:7], v[6:7], v[16:17] op_sel_hi:[1,0]
	v_cvt_pk_bf16_f32 v10, v10, v11
	v_cvt_pk_bf16_f32 v11, v20, v21
	global_store_dwordx4 v[18:19], v[8:11], off
	v_pk_mul_f32 v[4:5], v[4:5], v[16:17] op_sel_hi:[1,0]
	s_nop 0
	v_pk_mul_f32 v[8:9], v[2:3], v[16:17] op_sel_hi:[1,0]
	v_pk_mul_f32 v[2:3], v[0:1], v[16:17] op_sel_hi:[1,0]
	v_cvt_pk_bf16_f32 v0, v4, v5
	v_cvt_pk_bf16_f32 v1, v6, v7
	s_nop 0
	v_cvt_pk_bf16_f32 v2, v2, v3
	v_cvt_pk_bf16_f32 v3, v8, v9
	global_store_dwordx4 v[18:19], v[0:3], off offset:256
	s_cbranch_vccnz .LBB0_1231
	s_andn2_b64 vcc, exec, s[0:1]
	s_cbranch_vccnz .LBB0_1230
	s_nop 0
	s_branch .LBB0_1230

.LBB0_1829:
	s_lshl_b32 s1, s1, 10
	v_add_u32_e32 v160, s1, v155
	ds_read_b32 v153, v160
	ds_read_b32 v174, v160 offset:64
	ds_read_b32 v176, v160 offset:128
	ds_read_b32 v178, v160 offset:192
	ds_read_b32 v180, v160 offset:512
	ds_read_b32 v182, v160 offset:576
	ds_read_b32 v184, v160 offset:640
	ds_read_b32 v186, v160 offset:704
	s_waitcnt lgkmcnt(0)
	s_cmp_gt_i32 s0, 7
	v_lshl_add_u32 v150, s6, 8, v131
	s_cselect_b64 s[42:43], -1, 0
	s_mov_b64 s[6:7], -1
	s_and_b64 vcc, exec, s[42:43]
	v_ashrrev_i32_e32 v151, 31, v150
	v_lshlrev_b32_e32 v140, 1, v130
	s_cbranch_vccz .LBB0_1831
	v_lshlrev_b64 v[162:163], 11, v[150:151]
	v_lshl_add_u64 v[162:163], s[22:23], 0, v[162:163]
	s_lshl_b32 s8, s0, 9
	v_lshl_add_u64 v[162:163], v[162:163], 0, s[8:9]
	s_lshl_b32 s8, s57, 1
	v_lshl_add_u64 v[162:163], v[162:163], 0, s[8:9]
	s_waitcnt lgkmcnt(0)
	v_mov_b32_e32 v152, v153
	v_lshl_add_u64 v[166:167], v[162:163], 0, v[140:141]
	v_pk_mul_f32 v[164:165], v[126:127], v[152:153] op_sel_hi:[1,0]
	v_pk_mul_f32 v[162:163], v[124:125], v[152:153] op_sel_hi:[1,0]
	v_pk_mul_f32 v[168:169], v[122:123], v[152:153] op_sel_hi:[1,0]
	v_pk_mul_f32 v[170:171], v[120:121], v[152:153] op_sel_hi:[1,0]
	v_cvt_pk_bf16_f32 v162, v162, v163
	v_cvt_pk_bf16_f32 v163, v164, v165
	s_mov_b64 s[6:7], 0
	v_cvt_pk_bf16_f32 v164, v170, v171
	v_cvt_pk_bf16_f32 v165, v168, v169
	global_store_dwordx4 v[166:167], v[162:165], off offset:-4096
	v_pk_mul_f32 v[168:169], v[114:115], v[152:153] op_sel_hi:[1,0]
	v_pk_mul_f32 v[170:171], v[112:113], v[152:153] op_sel_hi:[1,0]
	v_pk_mul_f32 v[164:165], v[118:119], v[152:153] op_sel_hi:[1,0]
	v_pk_mul_f32 v[162:163], v[116:117], v[152:153] op_sel_hi:[1,0]
	s_nop 0
	v_cvt_pk_bf16_f32 v162, v162, v163
	v_cvt_pk_bf16_f32 v163, v164, v165
	v_cvt_pk_bf16_f32 v164, v170, v171
	v_cvt_pk_bf16_f32 v165, v168, v169
	global_store_dwordx4 v[166:167], v[162:165], off offset:-3840

.LBB0_1833:
	s_nop 1
	v_mov_b32_e32 v114, v174
	s_nop 0
	v_or_b32_e32 v112, 16, v150
	v_cndmask_b32_e64 v113, 0, 1, s[42:43]
	s_mov_b64 s[44:45], -1
	v_cmp_ne_u32_e64 s[6:7], 1, v113
	s_andn2_b64 vcc, exec, s[42:43]
	v_ashrrev_i32_e32 v113, 31, v112
	s_cbranch_vccnz .LBB0_1835
	v_lshlrev_b64 v[116:117], 11, v[112:113]
	v_lshl_add_u64 v[116:117], s[22:23], 0, v[116:117]
	s_lshl_b32 s8, s0, 9
	v_lshl_add_u64 v[116:117], v[116:117], 0, s[8:9]
	s_lshl_b32 s8, s57, 1
	v_lshl_add_u64 v[116:117], v[116:117], 0, s[8:9]
	v_lshl_add_u64 v[120:121], v[116:117], 0, v[140:141]
	s_waitcnt lgkmcnt(0)
	v_pk_mul_f32 v[118:119], v[110:111], v[114:115] op_sel_hi:[1,0]
	v_pk_mul_f32 v[116:117], v[108:109], v[114:115] op_sel_hi:[1,0]
	v_pk_mul_f32 v[122:123], v[106:107], v[114:115] op_sel_hi:[1,0]
	v_pk_mul_f32 v[124:125], v[104:105], v[114:115] op_sel_hi:[1,0]
	v_cvt_pk_bf16_f32 v116, v116, v117
	v_cvt_pk_bf16_f32 v117, v118, v119
	s_mov_b64 s[44:45], 0
	v_cvt_pk_bf16_f32 v118, v124, v125
	v_cvt_pk_bf16_f32 v119, v122, v123
	global_store_dwordx4 v[120:121], v[116:119], off offset:-4096
	v_pk_mul_f32 v[122:123], v[98:99], v[114:115] op_sel_hi:[1,0]
	v_pk_mul_f32 v[124:125], v[96:97], v[114:115] op_sel_hi:[1,0]
	v_pk_mul_f32 v[118:119], v[102:103], v[114:115] op_sel_hi:[1,0]
	v_pk_mul_f32 v[116:117], v[100:101], v[114:115] op_sel_hi:[1,0]
	s_nop 0
	v_cvt_pk_bf16_f32 v116, v116, v117
	v_cvt_pk_bf16_f32 v117, v118, v119
	v_cvt_pk_bf16_f32 v118, v124, v125
	v_cvt_pk_bf16_f32 v119, v122, v123
	global_store_dwordx4 v[120:121], v[116:119], off offset:-3840

.LBB0_1837:
	s_nop 1
	v_mov_b32_e32 v98, v176
	s_nop 0
	v_or_b32_e32 v96, 32, v150
	s_mov_b64 s[42:43], -1
	s_and_b64 vcc, exec, s[6:7]
	v_ashrrev_i32_e32 v97, 31, v96
	s_cbranch_vccnz .LBB0_1839
	v_lshlrev_b64 v[100:101], 11, v[96:97]
	v_lshl_add_u64 v[100:101], s[22:23], 0, v[100:101]
	s_lshl_b32 s8, s0, 9
	v_lshl_add_u64 v[100:101], v[100:101], 0, s[8:9]
	s_lshl_b32 s8, s57, 1
	v_lshl_add_u64 v[100:101], v[100:101], 0, s[8:9]
	v_lshl_add_u64 v[104:105], v[100:101], 0, v[140:141]
	s_waitcnt lgkmcnt(0)
	v_pk_mul_f32 v[102:103], v[94:95], v[98:99] op_sel_hi:[1,0]
	v_pk_mul_f32 v[100:101], v[92:93], v[98:99] op_sel_hi:[1,0]
	v_pk_mul_f32 v[106:107], v[90:91], v[98:99] op_sel_hi:[1,0]
	v_pk_mul_f32 v[108:109], v[88:89], v[98:99] op_sel_hi:[1,0]
	v_cvt_pk_bf16_f32 v100, v100, v101
	v_cvt_pk_bf16_f32 v101, v102, v103
	s_mov_b64 s[42:43], 0
	v_cvt_pk_bf16_f32 v102, v108, v109
	v_cvt_pk_bf16_f32 v103, v106, v107
	global_store_dwordx4 v[104:105], v[100:103], off offset:-4096
	v_pk_mul_f32 v[106:107], v[82:83], v[98:99] op_sel_hi:[1,0]
	v_pk_mul_f32 v[108:109], v[80:81], v[98:99] op_sel_hi:[1,0]
	v_pk_mul_f32 v[102:103], v[86:87], v[98:99] op_sel_hi:[1,0]
	v_pk_mul_f32 v[100:101], v[84:85], v[98:99] op_sel_hi:[1,0]
	s_nop 0
	v_cvt_pk_bf16_f32 v100, v100, v101
	v_cvt_pk_bf16_f32 v101, v102, v103
	v_cvt_pk_bf16_f32 v102, v108, v109
	v_cvt_pk_bf16_f32 v103, v106, v107
	global_store_dwordx4 v[104:105], v[100:103], off offset:-3840

.LBB0_1841:
	s_nop 1
	v_mov_b32_e32 v82, v178
	s_nop 0
	v_or_b32_e32 v80, 48, v150
	s_mov_b64 s[42:43], -1
	s_and_b64 vcc, exec, s[6:7]
	v_ashrrev_i32_e32 v81, 31, v80
	s_cbranch_vccnz .LBB0_1843
	v_lshlrev_b64 v[84:85], 11, v[80:81]
	v_lshl_add_u64 v[84:85], s[22:23], 0, v[84:85]
	s_lshl_b32 s8, s0, 9
	v_lshl_add_u64 v[84:85], v[84:85], 0, s[8:9]
	s_lshl_b32 s8, s57, 1
	v_lshl_add_u64 v[84:85], v[84:85], 0, s[8:9]
	v_lshl_add_u64 v[88:89], v[84:85], 0, v[140:141]
	s_waitcnt lgkmcnt(0)
	v_pk_mul_f32 v[86:87], v[78:79], v[82:83] op_sel_hi:[1,0]
	v_pk_mul_f32 v[84:85], v[76:77], v[82:83] op_sel_hi:[1,0]
	v_pk_mul_f32 v[90:91], v[74:75], v[82:83] op_sel_hi:[1,0]
	v_pk_mul_f32 v[92:93], v[72:73], v[82:83] op_sel_hi:[1,0]
	v_cvt_pk_bf16_f32 v84, v84, v85
	v_cvt_pk_bf16_f32 v85, v86, v87
	s_mov_b64 s[42:43], 0
	v_cvt_pk_bf16_f32 v86, v92, v93
	v_cvt_pk_bf16_f32 v87, v90, v91
	global_store_dwordx4 v[88:89], v[84:87], off offset:-4096
	v_pk_mul_f32 v[90:91], v[66:67], v[82:83] op_sel_hi:[1,0]
	v_pk_mul_f32 v[92:93], v[64:65], v[82:83] op_sel_hi:[1,0]
	v_pk_mul_f32 v[86:87], v[70:71], v[82:83] op_sel_hi:[1,0]
	v_pk_mul_f32 v[84:85], v[68:69], v[82:83] op_sel_hi:[1,0]
	s_nop 0
	v_cvt_pk_bf16_f32 v84, v84, v85
	v_cvt_pk_bf16_f32 v85, v86, v87
	v_cvt_pk_bf16_f32 v86, v92, v93
	v_cvt_pk_bf16_f32 v87, v90, v91
	global_store_dwordx4 v[88:89], v[84:87], off offset:-3840

.LBB0_1845:
	s_nop 1
	v_mov_b32_e32 v66, v180
	s_nop 0
	v_add_u32_e32 v64, 0x80, v150
	s_mov_b64 s[42:43], -1
	s_and_b64 vcc, exec, s[6:7]
	v_ashrrev_i32_e32 v65, 31, v64
	s_cbranch_vccnz .LBB0_1847
	v_lshlrev_b64 v[68:69], 11, v[64:65]
	v_lshl_add_u64 v[68:69], s[22:23], 0, v[68:69]
	s_lshl_b32 s8, s0, 9
	v_lshl_add_u64 v[68:69], v[68:69], 0, s[8:9]
	s_lshl_b32 s8, s57, 1
	v_lshl_add_u64 v[68:69], v[68:69], 0, s[8:9]
	v_lshl_add_u64 v[72:73], v[68:69], 0, v[140:141]
	s_waitcnt lgkmcnt(0)
	v_pk_mul_f32 v[70:71], v[62:63], v[66:67] op_sel_hi:[1,0]
	v_pk_mul_f32 v[68:69], v[60:61], v[66:67] op_sel_hi:[1,0]
	v_pk_mul_f32 v[74:75], v[58:59], v[66:67] op_sel_hi:[1,0]
	v_pk_mul_f32 v[76:77], v[56:57], v[66:67] op_sel_hi:[1,0]
	v_cvt_pk_bf16_f32 v68, v68, v69
	v_cvt_pk_bf16_f32 v69, v70, v71
	s_mov_b64 s[42:43], 0
	v_cvt_pk_bf16_f32 v70, v76, v77
	v_cvt_pk_bf16_f32 v71, v74, v75
	global_store_dwordx4 v[72:73], v[68:71], off offset:-4096
	v_pk_mul_f32 v[74:75], v[50:51], v[66:67] op_sel_hi:[1,0]
	v_pk_mul_f32 v[76:77], v[48:49], v[66:67] op_sel_hi:[1,0]
	v_pk_mul_f32 v[70:71], v[54:55], v[66:67] op_sel_hi:[1,0]
	v_pk_mul_f32 v[68:69], v[52:53], v[66:67] op_sel_hi:[1,0]
	s_nop 0
	v_cvt_pk_bf16_f32 v68, v68, v69
	v_cvt_pk_bf16_f32 v69, v70, v71
	v_cvt_pk_bf16_f32 v70, v76, v77
	v_cvt_pk_bf16_f32 v71, v74, v75
	global_store_dwordx4 v[72:73], v[68:71], off offset:-3840

.LBB0_1849:
	s_nop 1
	v_mov_b32_e32 v50, v182
	s_nop 0
	v_add_u32_e32 v48, 0x90, v150
	s_mov_b64 s[42:43], -1
	s_and_b64 vcc, exec, s[6:7]
	v_ashrrev_i32_e32 v49, 31, v48
	s_cbranch_vccnz .LBB0_1851
	v_lshlrev_b64 v[52:53], 11, v[48:49]
	v_lshl_add_u64 v[52:53], s[22:23], 0, v[52:53]
	s_lshl_b32 s8, s0, 9
	v_lshl_add_u64 v[52:53], v[52:53], 0, s[8:9]
	s_lshl_b32 s8, s57, 1
	v_lshl_add_u64 v[52:53], v[52:53], 0, s[8:9]
	v_lshl_add_u64 v[56:57], v[52:53], 0, v[140:141]
	s_waitcnt lgkmcnt(0)
	v_pk_mul_f32 v[54:55], v[46:47], v[50:51] op_sel_hi:[1,0]
	v_pk_mul_f32 v[52:53], v[44:45], v[50:51] op_sel_hi:[1,0]
	v_pk_mul_f32 v[58:59], v[42:43], v[50:51] op_sel_hi:[1,0]
	v_pk_mul_f32 v[60:61], v[40:41], v[50:51] op_sel_hi:[1,0]
	v_cvt_pk_bf16_f32 v52, v52, v53
	v_cvt_pk_bf16_f32 v53, v54, v55
	s_mov_b64 s[42:43], 0
	v_cvt_pk_bf16_f32 v54, v60, v61
	v_cvt_pk_bf16_f32 v55, v58, v59
	global_store_dwordx4 v[56:57], v[52:55], off offset:-4096
	v_pk_mul_f32 v[58:59], v[34:35], v[50:51] op_sel_hi:[1,0]
	v_pk_mul_f32 v[60:61], v[32:33], v[50:51] op_sel_hi:[1,0]
	v_pk_mul_f32 v[54:55], v[38:39], v[50:51] op_sel_hi:[1,0]
	v_pk_mul_f32 v[52:53], v[36:37], v[50:51] op_sel_hi:[1,0]
	s_nop 0
	v_cvt_pk_bf16_f32 v52, v52, v53
	v_cvt_pk_bf16_f32 v53, v54, v55
	v_cvt_pk_bf16_f32 v54, v60, v61
	v_cvt_pk_bf16_f32 v55, v58, v59
	global_store_dwordx4 v[56:57], v[52:55], off offset:-3840

.LBB0_1853:
	s_nop 1
	v_mov_b32_e32 v34, v184
	s_nop 0
	v_add_u32_e32 v32, 0xa0, v150
	s_mov_b64 s[42:43], -1
	s_and_b64 vcc, exec, s[6:7]
	v_ashrrev_i32_e32 v33, 31, v32
	s_cbranch_vccnz .LBB0_1855
	v_lshlrev_b64 v[36:37], 11, v[32:33]
	v_lshl_add_u64 v[36:37], s[22:23], 0, v[36:37]
	s_lshl_b32 s8, s0, 9
	v_lshl_add_u64 v[36:37], v[36:37], 0, s[8:9]
	s_lshl_b32 s8, s57, 1
	v_lshl_add_u64 v[36:37], v[36:37], 0, s[8:9]
	v_lshl_add_u64 v[40:41], v[36:37], 0, v[140:141]
	s_waitcnt lgkmcnt(0)
	v_pk_mul_f32 v[38:39], v[30:31], v[34:35] op_sel_hi:[1,0]
	v_pk_mul_f32 v[36:37], v[28:29], v[34:35] op_sel_hi:[1,0]
	v_pk_mul_f32 v[42:43], v[26:27], v[34:35] op_sel_hi:[1,0]
	v_pk_mul_f32 v[44:45], v[24:25], v[34:35] op_sel_hi:[1,0]
	v_cvt_pk_bf16_f32 v36, v36, v37
	v_cvt_pk_bf16_f32 v37, v38, v39
	s_mov_b64 s[42:43], 0
	v_cvt_pk_bf16_f32 v38, v44, v45
	v_cvt_pk_bf16_f32 v39, v42, v43
	global_store_dwordx4 v[40:41], v[36:39], off offset:-4096
	v_pk_mul_f32 v[42:43], v[18:19], v[34:35] op_sel_hi:[1,0]
	v_pk_mul_f32 v[44:45], v[16:17], v[34:35] op_sel_hi:[1,0]
	v_pk_mul_f32 v[38:39], v[22:23], v[34:35] op_sel_hi:[1,0]
	v_pk_mul_f32 v[36:37], v[20:21], v[34:35] op_sel_hi:[1,0]
	s_nop 0
	v_cvt_pk_bf16_f32 v36, v36, v37
	v_cvt_pk_bf16_f32 v37, v38, v39
	v_cvt_pk_bf16_f32 v38, v44, v45
	v_cvt_pk_bf16_f32 v39, v42, v43
	global_store_dwordx4 v[40:41], v[36:39], off offset:-3840

.LBB0_1857:
	s_nop 1
	v_mov_b32_e32 v18, v186
	s_nop 0
	v_add_u32_e32 v16, 0xb0, v150
	s_mov_b64 s[42:43], -1
	s_and_b64 vcc, exec, s[6:7]
	v_ashrrev_i32_e32 v17, 31, v16
	s_cbranch_vccz .LBB0_1860
	s_andn2_b64 vcc, exec, s[42:43]
	s_cbranch_vccz .LBB0_1861
